# gla_pass2 per-head state reload: 17 loads issued together instead of 6 serial round trips
# speedup vs baseline: 1.0072x; 1.0072x over previous
; #define LAS __attribute__((address_space(3)))
; __device__ __forceinline__ unsigned f2bf(float f) { return pk2(f, f) & 0xffffu; }
; template <int PASS>
; __device__ __forceinline__ void gla_pass(CArgs& a, LAS unsigned char* lds, int l, int panel) {
;     ...
;         const int h = it >> 2, c = it & 3, row0 = c * 64;
;         if (c == 0) {
;             bg = a.in[14][l * 256 + h * 64 + d_];
;             Sg = (float*)(ws + WS_GLAS) + ((size_t)panel * 4 + h) * 8192;
; #pragma unroll
;             for (int k = 0; k < 4; ++k) {
;                 const int et = wh * 4 + k;
; #pragma unroll
;                 for (int r = 0; r < 4; ++r) {
;                     const int e = 16 * et + 4 * fq + r, d = 16 * wq + fr;
;                     if (PASS == 2) { const float v = Sg[e * 64 + d]; st[k][r] = v; *(LAS bf16_t*)(lds + GL_ST + e * GRS + d * 2) = (bf16_t)f2bf(v); }
;                     else st[k][r] = 0.f;
;                 }
;             }
;             dprod = 1.f;
;         }
.LBB0_376:
	s_add_i32 s1, s4, -1
	s_lshr_b32 s19, s1, 2
	s_and_b32 s18, s1, 3
	s_cmp_lg_u32 s18, 0
	s_cbranch_scc1 .LBB0_378
	s_lshl_b32 s36, s19, 13
	s_lshl_b64 s[8:9], s[36:37], 2
	v_lshl_add_u32 v0, s19, 6, v150
	s_add_u32 s84, s20, s8
	s_addc_u32 s85, s21, s9
	s_waitcnt lgkmcnt(0)
	v_lshl_add_u64 v[70:71], v[0:1], 2, s[38:39]
	global_load_dword v174, v[70:71], off
	v_lshl_add_u64 v[70:71], v[94:95], 2, s[84:85]
	global_load_dword v2, v[70:71], off
	v_lshl_add_u64 v[70:71], v[98:99], 2, s[84:85]
	global_load_dword v3, v[70:71], off
	v_lshl_add_u64 v[70:71], v[100:101], 2, s[84:85]
	global_load_dword v4, v[70:71], off
	v_lshl_add_u64 v[70:71], v[102:103], 2, s[84:85]
	global_load_dword v5, v[70:71], off
	v_lshl_add_u64 v[70:71], v[104:105], 2, s[84:85]
	global_load_dword v6, v[70:71], off
	v_lshl_add_u64 v[70:71], v[106:107], 2, s[84:85]
	global_load_dword v7, v[70:71], off
	v_lshl_add_u64 v[70:71], v[108:109], 2, s[84:85]
	global_load_dword v8, v[70:71], off
	v_lshl_add_u64 v[70:71], v[110:111], 2, s[84:85]
	global_load_dword v9, v[70:71], off
	v_lshl_add_u64 v[70:71], v[112:113], 2, s[84:85]
	global_load_dword v10, v[70:71], off
	v_lshl_add_u64 v[70:71], v[114:115], 2, s[84:85]
	global_load_dword v11, v[70:71], off
	v_lshl_add_u64 v[70:71], v[116:117], 2, s[84:85]
	global_load_dword v12, v[70:71], off
	v_lshl_add_u64 v[70:71], v[118:119], 2, s[84:85]
	global_load_dword v13, v[70:71], off
	v_lshl_add_u64 v[70:71], v[120:121], 2, s[84:85]
	global_load_dword v14, v[70:71], off
	v_lshl_add_u64 v[70:71], v[122:123], 2, s[84:85]
	global_load_dword v15, v[70:71], off
	v_lshl_add_u64 v[70:71], v[124:125], 2, s[84:85]
	global_load_dword v16, v[70:71], off
	v_lshl_add_u64 v[70:71], v[126:127], 2, s[84:85]
	global_load_dword v17, v[70:71], off
	v_add_u32_e32 v71, v153, v163
	v_add_u32_e32 v72, v153, v166
	s_waitcnt vmcnt(0)
	v_cvt_pk_bf16_f32 v0, v2, v2
	s_nop 0
	ds_write_b16 v71, v0 offset:55296
	v_cvt_pk_bf16_f32 v0, v3, v3
	s_nop 0
	ds_write_b16 v71, v0 offset:55440
	v_cvt_pk_bf16_f32 v0, v4, v4
	s_nop 0
	ds_write_b16 v71, v0 offset:55584
	v_cvt_pk_bf16_f32 v0, v5, v5
	s_nop 0
	ds_write_b16 v71, v0 offset:55728
	v_cvt_pk_bf16_f32 v0, v6, v6
	s_nop 0
	ds_write_b16 v71, v0 offset:57600
	v_cvt_pk_bf16_f32 v0, v7, v7
	s_nop 0
	ds_write_b16 v171, v0 offset:55296
	v_cvt_pk_bf16_f32 v0, v8, v8
	s_nop 0
	ds_write_b16 v171, v0 offset:55440
	v_cvt_pk_bf16_f32 v0, v9, v9
	s_nop 0
	ds_write_b16 v171, v0 offset:55584
	v_cvt_pk_bf16_f32 v0, v10, v10
	s_nop 0
	ds_write_b16 v171, v0 offset:57456
	v_cvt_pk_bf16_f32 v0, v11, v11
	s_nop 0
	ds_write_b16 v171, v0 offset:57600
	v_cvt_pk_bf16_f32 v0, v12, v12
	s_nop 0
	ds_write_b16 v72, v0 offset:55296
	v_cvt_pk_bf16_f32 v0, v13, v13
	s_nop 0
	ds_write_b16 v72, v0 offset:55440
	v_cvt_pk_bf16_f32 v0, v14, v14
	s_nop 0
	ds_write_b16 v72, v0 offset:57312
	v_cvt_pk_bf16_f32 v0, v15, v15
	s_nop 0
	ds_write_b16 v72, v0 offset:57456
	v_cvt_pk_bf16_f32 v0, v16, v16
	s_nop 0
	ds_write_b16 v72, v0 offset:57600
	v_cvt_pk_bf16_f32 v0, v17, v17
	s_nop 0
	ds_write_b16 v72, v0 offset:57744
